# hgrn_b state scan: 32 steps (64 loads) in flight per batch instead of 8 steps (two latency round trips instead of eight)
# baseline (speedup 1.0000x reference)
.LBB0_264:
	v_lshl_add_u64 v[10:11], s[20:21], 0, v[4:5]
	v_lshl_add_u64 v[6:7], s[20:21], 0, v[0:1]
	v_add_u32_e32 v8, s8, v14
	v_ashrrev_i32_e32 v9, 31, v8
	v_lshl_add_u64 v[8:9], v[8:9], 2, s[38:39]
	s_mov_b64 s[22:23], 0x1000
	v_lshl_add_u64 v[240:241], v[8:9], 0, s[22:23]
	s_mov_b32 s22, 0xc400000
	s_mov_b32 s23, 0
	global_load_dword v60, v[8:9], off
	v_lshl_add_u64 v[16:17], v[6:7], 0, s[22:23]
	global_load_dword v61, v[16:17], off
	s_add_u32 s22, s22, 0x4000
	global_load_dword v62, v[8:9], off offset:256
	v_lshl_add_u64 v[16:17], v[6:7], 0, s[22:23]
	global_load_dword v63, v[16:17], off
	s_add_u32 s22, s22, 0x4000
	global_load_dword v64, v[8:9], off offset:512
	v_lshl_add_u64 v[16:17], v[6:7], 0, s[22:23]
	global_load_dword v65, v[16:17], off
	s_add_u32 s22, s22, 0x4000
	global_load_dword v66, v[8:9], off offset:768
	v_lshl_add_u64 v[16:17], v[6:7], 0, s[22:23]
	global_load_dword v67, v[16:17], off
	s_add_u32 s22, s22, 0x4000
	global_load_dword v68, v[8:9], off offset:1024
	v_lshl_add_u64 v[16:17], v[6:7], 0, s[22:23]
	global_load_dword v69, v[16:17], off
	s_add_u32 s22, s22, 0x4000
	global_load_dword v70, v[8:9], off offset:1280
	v_lshl_add_u64 v[16:17], v[6:7], 0, s[22:23]
	global_load_dword v71, v[16:17], off
	s_add_u32 s22, s22, 0x4000
	global_load_dword v72, v[8:9], off offset:1536
	v_lshl_add_u64 v[16:17], v[6:7], 0, s[22:23]
	global_load_dword v73, v[16:17], off
	s_add_u32 s22, s22, 0x4000
	global_load_dword v74, v[8:9], off offset:1792
	v_lshl_add_u64 v[16:17], v[6:7], 0, s[22:23]
	global_load_dword v75, v[16:17], off
	s_add_u32 s22, s22, 0x4000
	global_load_dword v192, v[8:9], off offset:2048
	v_lshl_add_u64 v[16:17], v[6:7], 0, s[22:23]
	global_load_dword v193, v[16:17], off
	s_add_u32 s22, s22, 0x4000
	global_load_dword v194, v[8:9], off offset:2304
	v_lshl_add_u64 v[16:17], v[6:7], 0, s[22:23]
	global_load_dword v195, v[16:17], off
	s_add_u32 s22, s22, 0x4000
	global_load_dword v196, v[8:9], off offset:2560
	v_lshl_add_u64 v[16:17], v[6:7], 0, s[22:23]
	global_load_dword v197, v[16:17], off
	s_add_u32 s22, s22, 0x4000
	global_load_dword v198, v[8:9], off offset:2816
	v_lshl_add_u64 v[16:17], v[6:7], 0, s[22:23]
	global_load_dword v199, v[16:17], off
	s_add_u32 s22, s22, 0x4000
	global_load_dword v200, v[8:9], off offset:3072
	v_lshl_add_u64 v[16:17], v[6:7], 0, s[22:23]
	global_load_dword v201, v[16:17], off
	s_add_u32 s22, s22, 0x4000
	global_load_dword v202, v[8:9], off offset:3328
	v_lshl_add_u64 v[16:17], v[6:7], 0, s[22:23]
	global_load_dword v203, v[16:17], off
	s_add_u32 s22, s22, 0x4000
	global_load_dword v204, v[8:9], off offset:3584
	v_lshl_add_u64 v[16:17], v[6:7], 0, s[22:23]
	global_load_dword v205, v[16:17], off
	s_add_u32 s22, s22, 0x4000
	global_load_dword v206, v[8:9], off offset:3840
	v_lshl_add_u64 v[16:17], v[6:7], 0, s[22:23]
	global_load_dword v207, v[16:17], off
	s_add_u32 s22, s22, 0x4000
	global_load_dword v208, v[240:241], off
	v_lshl_add_u64 v[16:17], v[6:7], 0, s[22:23]
	global_load_dword v209, v[16:17], off
	s_add_u32 s22, s22, 0x4000
	global_load_dword v210, v[240:241], off offset:256
	v_lshl_add_u64 v[16:17], v[6:7], 0, s[22:23]
	global_load_dword v211, v[16:17], off
	s_add_u32 s22, s22, 0x4000
	global_load_dword v212, v[240:241], off offset:512
	v_lshl_add_u64 v[16:17], v[6:7], 0, s[22:23]
	global_load_dword v213, v[16:17], off
	s_add_u32 s22, s22, 0x4000
	global_load_dword v214, v[240:241], off offset:768
	v_lshl_add_u64 v[16:17], v[6:7], 0, s[22:23]
	global_load_dword v215, v[16:17], off
	s_add_u32 s22, s22, 0x4000
	global_load_dword v216, v[240:241], off offset:1024
	v_lshl_add_u64 v[16:17], v[6:7], 0, s[22:23]
	global_load_dword v217, v[16:17], off
	s_add_u32 s22, s22, 0x4000
	global_load_dword v218, v[240:241], off offset:1280
	v_lshl_add_u64 v[16:17], v[6:7], 0, s[22:23]
	global_load_dword v219, v[16:17], off
	s_add_u32 s22, s22, 0x4000
	global_load_dword v220, v[240:241], off offset:1536
	v_lshl_add_u64 v[16:17], v[6:7], 0, s[22:23]
	global_load_dword v221, v[16:17], off
	s_add_u32 s22, s22, 0x4000
	global_load_dword v222, v[240:241], off offset:1792
	v_lshl_add_u64 v[16:17], v[6:7], 0, s[22:23]
	global_load_dword v223, v[16:17], off
	s_add_u32 s22, s22, 0x4000
	global_load_dword v224, v[240:241], off offset:2048
	v_lshl_add_u64 v[16:17], v[6:7], 0, s[22:23]
	global_load_dword v225, v[16:17], off
	s_add_u32 s22, s22, 0x4000
	global_load_dword v226, v[240:241], off offset:2304
	v_lshl_add_u64 v[16:17], v[6:7], 0, s[22:23]
	global_load_dword v227, v[16:17], off
	s_add_u32 s22, s22, 0x4000
	global_load_dword v228, v[240:241], off offset:2560
	v_lshl_add_u64 v[16:17], v[6:7], 0, s[22:23]
	global_load_dword v229, v[16:17], off
	s_add_u32 s22, s22, 0x4000
	global_load_dword v230, v[240:241], off offset:2816
	v_lshl_add_u64 v[16:17], v[6:7], 0, s[22:23]
	global_load_dword v231, v[16:17], off
	s_add_u32 s22, s22, 0x4000
	global_load_dword v232, v[240:241], off offset:3072
	v_lshl_add_u64 v[16:17], v[6:7], 0, s[22:23]
	global_load_dword v233, v[16:17], off
	s_add_u32 s22, s22, 0x4000
	global_load_dword v234, v[240:241], off offset:3328
	v_lshl_add_u64 v[16:17], v[6:7], 0, s[22:23]
	global_load_dword v235, v[16:17], off
	s_add_u32 s22, s22, 0x4000
	global_load_dword v236, v[240:241], off offset:3584
	v_lshl_add_u64 v[16:17], v[6:7], 0, s[22:23]
	global_load_dword v237, v[16:17], off
	s_add_u32 s22, s22, 0x4000
	global_load_dword v238, v[240:241], off offset:3840
	v_lshl_add_u64 v[16:17], v[6:7], 0, s[22:23]
	global_load_dword v239, v[16:17], off
	s_mov_b32 s22, 0x1c000000
	v_cvt_pk_bf16_f32 v18, v15, v2
	v_lshl_add_u64 v[16:17], v[10:11], 0, s[22:23]
	global_store_short v[16:17], v18, off
	s_add_u32 s22, s22, 0x2000
	s_waitcnt vmcnt(63)
	v_fmac_f32_e32 v61, v15, v60
	v_cvt_pk_bf16_f32 v18, v61, v2
	v_lshl_add_u64 v[16:17], v[10:11], 0, s[22:23]
	global_store_short v[16:17], v18, off
	s_add_u32 s22, s22, 0x2000
	s_waitcnt vmcnt(62)
	v_fmac_f32_e32 v63, v61, v62
	v_cvt_pk_bf16_f32 v18, v63, v2
	v_lshl_add_u64 v[16:17], v[10:11], 0, s[22:23]
	global_store_short v[16:17], v18, off
	s_add_u32 s22, s22, 0x2000
	s_waitcnt vmcnt(61)
	v_fmac_f32_e32 v65, v63, v64
	v_cvt_pk_bf16_f32 v18, v65, v2
	v_lshl_add_u64 v[16:17], v[10:11], 0, s[22:23]
	global_store_short v[16:17], v18, off
	s_add_u32 s22, s22, 0x2000
	s_waitcnt vmcnt(60)
	v_fmac_f32_e32 v67, v65, v66
	v_cvt_pk_bf16_f32 v18, v67, v2
	v_lshl_add_u64 v[16:17], v[10:11], 0, s[22:23]
	global_store_short v[16:17], v18, off
	s_add_u32 s22, s22, 0x2000
	s_waitcnt vmcnt(59)
	v_fmac_f32_e32 v69, v67, v68
	v_cvt_pk_bf16_f32 v18, v69, v2
	v_lshl_add_u64 v[16:17], v[10:11], 0, s[22:23]
	global_store_short v[16:17], v18, off
	s_add_u32 s22, s22, 0x2000
	s_waitcnt vmcnt(58)
	v_fmac_f32_e32 v71, v69, v70
	v_cvt_pk_bf16_f32 v18, v71, v2
	v_lshl_add_u64 v[16:17], v[10:11], 0, s[22:23]
	global_store_short v[16:17], v18, off
	s_add_u32 s22, s22, 0x2000
	s_waitcnt vmcnt(57)
	v_fmac_f32_e32 v73, v71, v72
	v_cvt_pk_bf16_f32 v18, v73, v2
	v_lshl_add_u64 v[16:17], v[10:11], 0, s[22:23]
	global_store_short v[16:17], v18, off
	s_add_u32 s22, s22, 0x2000
	s_waitcnt vmcnt(56)
	v_fmac_f32_e32 v75, v73, v74
	v_cvt_pk_bf16_f32 v18, v75, v2
	v_lshl_add_u64 v[16:17], v[10:11], 0, s[22:23]
	global_store_short v[16:17], v18, off
	s_add_u32 s22, s22, 0x2000
	s_waitcnt vmcnt(55)
	v_fmac_f32_e32 v193, v75, v192
	v_cvt_pk_bf16_f32 v18, v193, v2
	v_lshl_add_u64 v[16:17], v[10:11], 0, s[22:23]
	global_store_short v[16:17], v18, off
	s_add_u32 s22, s22, 0x2000
	s_waitcnt vmcnt(54)
	v_fmac_f32_e32 v195, v193, v194
	v_cvt_pk_bf16_f32 v18, v195, v2
	v_lshl_add_u64 v[16:17], v[10:11], 0, s[22:23]
	global_store_short v[16:17], v18, off
	s_add_u32 s22, s22, 0x2000
	s_waitcnt vmcnt(53)
	v_fmac_f32_e32 v197, v195, v196
	v_cvt_pk_bf16_f32 v18, v197, v2
	v_lshl_add_u64 v[16:17], v[10:11], 0, s[22:23]
	global_store_short v[16:17], v18, off
	s_add_u32 s22, s22, 0x2000
	s_waitcnt vmcnt(52)
	v_fmac_f32_e32 v199, v197, v198
	v_cvt_pk_bf16_f32 v18, v199, v2
	v_lshl_add_u64 v[16:17], v[10:11], 0, s[22:23]
	global_store_short v[16:17], v18, off
	s_add_u32 s22, s22, 0x2000
	s_waitcnt vmcnt(51)
	v_fmac_f32_e32 v201, v199, v200
	v_cvt_pk_bf16_f32 v18, v201, v2
	v_lshl_add_u64 v[16:17], v[10:11], 0, s[22:23]
	global_store_short v[16:17], v18, off
	s_add_u32 s22, s22, 0x2000
	s_waitcnt vmcnt(50)
	v_fmac_f32_e32 v203, v201, v202
	v_cvt_pk_bf16_f32 v18, v203, v2
	v_lshl_add_u64 v[16:17], v[10:11], 0, s[22:23]
	global_store_short v[16:17], v18, off
	s_add_u32 s22, s22, 0x2000
	s_waitcnt vmcnt(49)
	v_fmac_f32_e32 v205, v203, v204
	v_cvt_pk_bf16_f32 v18, v205, v2
	v_lshl_add_u64 v[16:17], v[10:11], 0, s[22:23]
	global_store_short v[16:17], v18, off
	s_add_u32 s22, s22, 0x2000
	s_waitcnt vmcnt(48)
	v_fmac_f32_e32 v207, v205, v206
	v_cvt_pk_bf16_f32 v18, v207, v2
	v_lshl_add_u64 v[16:17], v[10:11], 0, s[22:23]
	global_store_short v[16:17], v18, off
	s_add_u32 s22, s22, 0x2000
	s_waitcnt vmcnt(47)
	v_fmac_f32_e32 v209, v207, v208
	v_cvt_pk_bf16_f32 v18, v209, v2
	v_lshl_add_u64 v[16:17], v[10:11], 0, s[22:23]
	global_store_short v[16:17], v18, off
	s_add_u32 s22, s22, 0x2000
	s_waitcnt vmcnt(46)
	v_fmac_f32_e32 v211, v209, v210
	v_cvt_pk_bf16_f32 v18, v211, v2
	v_lshl_add_u64 v[16:17], v[10:11], 0, s[22:23]
	global_store_short v[16:17], v18, off
	s_add_u32 s22, s22, 0x2000
	s_waitcnt vmcnt(45)
	v_fmac_f32_e32 v213, v211, v212
	v_cvt_pk_bf16_f32 v18, v213, v2
	v_lshl_add_u64 v[16:17], v[10:11], 0, s[22:23]
	global_store_short v[16:17], v18, off
	s_add_u32 s22, s22, 0x2000
	s_waitcnt vmcnt(44)
	v_fmac_f32_e32 v215, v213, v214
	v_cvt_pk_bf16_f32 v18, v215, v2
	v_lshl_add_u64 v[16:17], v[10:11], 0, s[22:23]
	global_store_short v[16:17], v18, off
	s_add_u32 s22, s22, 0x2000
	s_waitcnt vmcnt(43)
	v_fmac_f32_e32 v217, v215, v216
	v_cvt_pk_bf16_f32 v18, v217, v2
	v_lshl_add_u64 v[16:17], v[10:11], 0, s[22:23]
	global_store_short v[16:17], v18, off
	s_add_u32 s22, s22, 0x2000
	s_waitcnt vmcnt(42)
	v_fmac_f32_e32 v219, v217, v218
	v_cvt_pk_bf16_f32 v18, v219, v2
	v_lshl_add_u64 v[16:17], v[10:11], 0, s[22:23]
	global_store_short v[16:17], v18, off
	s_add_u32 s22, s22, 0x2000
	s_waitcnt vmcnt(41)
	v_fmac_f32_e32 v221, v219, v220
	v_cvt_pk_bf16_f32 v18, v221, v2
	v_lshl_add_u64 v[16:17], v[10:11], 0, s[22:23]
	global_store_short v[16:17], v18, off
	s_add_u32 s22, s22, 0x2000
	s_waitcnt vmcnt(40)
	v_fmac_f32_e32 v223, v221, v222
	v_cvt_pk_bf16_f32 v18, v223, v2
	v_lshl_add_u64 v[16:17], v[10:11], 0, s[22:23]
	global_store_short v[16:17], v18, off
	s_add_u32 s22, s22, 0x2000
	s_waitcnt vmcnt(39)
	v_fmac_f32_e32 v225, v223, v224
	v_cvt_pk_bf16_f32 v18, v225, v2
	v_lshl_add_u64 v[16:17], v[10:11], 0, s[22:23]
	global_store_short v[16:17], v18, off
	s_add_u32 s22, s22, 0x2000
	s_waitcnt vmcnt(38)
	v_fmac_f32_e32 v227, v225, v226
	v_cvt_pk_bf16_f32 v18, v227, v2
	v_lshl_add_u64 v[16:17], v[10:11], 0, s[22:23]
	global_store_short v[16:17], v18, off
	s_add_u32 s22, s22, 0x2000
	s_waitcnt vmcnt(37)
	v_fmac_f32_e32 v229, v227, v228
	v_cvt_pk_bf16_f32 v18, v229, v2
	v_lshl_add_u64 v[16:17], v[10:11], 0, s[22:23]
	global_store_short v[16:17], v18, off
	s_add_u32 s22, s22, 0x2000
	s_waitcnt vmcnt(36)
	v_fmac_f32_e32 v231, v229, v230
	v_cvt_pk_bf16_f32 v18, v231, v2
	v_lshl_add_u64 v[16:17], v[10:11], 0, s[22:23]
	global_store_short v[16:17], v18, off
	s_add_u32 s22, s22, 0x2000
	s_waitcnt vmcnt(35)
	v_fmac_f32_e32 v233, v231, v232
	v_cvt_pk_bf16_f32 v18, v233, v2
	v_lshl_add_u64 v[16:17], v[10:11], 0, s[22:23]
	global_store_short v[16:17], v18, off
	s_add_u32 s22, s22, 0x2000
	s_waitcnt vmcnt(34)
	v_fmac_f32_e32 v235, v233, v234
	v_cvt_pk_bf16_f32 v18, v235, v2
	v_lshl_add_u64 v[16:17], v[10:11], 0, s[22:23]
	global_store_short v[16:17], v18, off
	s_add_u32 s22, s22, 0x2000
	s_waitcnt vmcnt(33)
	v_fmac_f32_e32 v237, v235, v236
	v_cvt_pk_bf16_f32 v18, v237, v2
	v_lshl_add_u64 v[16:17], v[10:11], 0, s[22:23]
	global_store_short v[16:17], v18, off
	s_waitcnt vmcnt(32)
	v_fmac_f32_e32 v239, v237, v238
	v_mov_b32_e32 v15, v239
	s_addk_i32 s8, 0x800
	s_mov_b64 s[22:23], 0x80000
	v_lshl_add_u64 v[0:1], v[0:1], 0, s[22:23]
	s_mov_b64 s[22:23], 0x40000
	v_lshl_add_u64 v[4:5], v[4:5], 0, s[22:23]
	s_cmpk_eq_i32 s8, 0x1000
	s_cbranch_scc0 .LBB0_264
	v_add_u32_e32 v3, s83, v3
	s_movk_i32 s8, 0x3fff
	v_cmp_lt_i32_e32 vcc, s8, v3
	s_or_b64 s[40:41], vcc, s[40:41]
	v_add_u16_e32 v13, s83, v13
	s_andn2_b64 exec, exec, s[40:41]
	s_cbranch_execnz .LBB0_263
